# P2: the 48 forget-gate cumulative sums run on the non-tanh waves (4-7) of CUs 0-11 instead of all waves of CUs 0-5, overlapping the tanh waves' token-shift work
# speedup vs baseline: 1.0152x; 1.0138x over previous
; __device__ __forceinline__ void phase_shift_cum(const Args& A, int gtid, int NGT, int gw, int lane) {
;     ...
;     const float* FL = (const float*)(ws + WS_FL); const float* b_f = A.in[14]; float* CUM = (float*)(ws + WS_CUM);
;     if (gw < BATCH * NH) {
;         const int b = gw / NH, h = gw % NH; const float bf = b_f[h];
;         const float* src = FL + ((size_t)b * T + lane * 64) * 256 + h; float zv[64];
; #pragma unroll
;         for (int i = 0; i < 64; ++i) zv[i] = src[(size_t)i * 256];
.LBB0_311:
	s_or_b64 exec, exec, s[4:5]
	s_ashr_i32 s0, s0, 6
	s_lshl_b32 s1, s1, 2
	s_add_i32 s4, s1, s0
	s_sub_i32 s4, s4, 4
	s_cmp_lt_u32 s0, 4
	s_cselect_b32 s4, 0x1000, s4
	s_cmp_lt_i32 s4, 48
	s_cbranch_scc0 .LBB0_313
	s_mul_hi_i32 s0, s4, 0x2aaaaaab
	s_lshr_b32 s1, s0, 31
	s_ashr_i32 s0, s0, 2
	s_add_i32 s0, s0, s1
	s_load_dwordx16 s[8:23], s[62:63], 0x40
	s_mul_i32 s1, s0, 24
	s_sub_i32 s6, s4, s1
	s_ashr_i32 s7, s6, 31
	s_lshl_b64 s[6:7], s[6:7], 2
	s_waitcnt lgkmcnt(0)
	s_add_u32 s8, s20, s6
	s_addc_u32 s9, s21, s7
	s_ashr_i32 s1, s0, 31
	s_lshl_b64 s[0:1], s[0:1], 22
	v_and_b32_e32 v2, 63, v14
	s_add_u32 s0, s34, s0
	v_mov_b32_e32 v1, 0
	s_addc_u32 s1, s35, s1
	v_lshlrev_b32_e32 v0, 16, v2
	v_lshl_add_u64 v[4:5], s[0:1], 0, v[0:1]
	global_load_dword v3, v1, s[8:9]
	v_lshl_add_u64 v[4:5], v[4:5], 0, s[6:7]
	s_mov_b64 s[0:1], 0x18200000
	v_lshl_add_u64 v[6:7], v[4:5], 0, s[0:1]
	s_mov_b32 s0, 0x18201000
	v_add_co_u32_e32 v8, vcc, s0, v4
	s_mov_b32 s0, 0x18202000
	s_nop 0
	v_addc_co_u32_e32 v9, vcc, 0, v5, vcc
	v_add_co_u32_e32 v10, vcc, s0, v4
	s_mov_b32 s0, 0x18203000
	s_nop 0
	v_addc_co_u32_e32 v11, vcc, 0, v5, vcc
	v_add_co_u32_e32 v12, vcc, s0, v4
	s_mov_b32 s0, 0x18204000
	s_nop 0
	v_addc_co_u32_e32 v13, vcc, 0, v5, vcc
	global_load_dword v0, v[8:9], off offset:-4096
	global_load_dword v18, v[8:9], off
	global_load_dword v22, v[8:9], off offset:1024
	global_load_dword v23, v[8:9], off offset:2048
	global_load_dword v27, v[8:9], off offset:3072
	global_load_dword v29, v[12:13], off offset:-4096
	global_load_dword v32, v[12:13], off
	global_load_dword v35, v[12:13], off offset:1024
	v_add_co_u32_e32 v8, vcc, s0, v4
	s_mov_b32 s0, 0x18205000
	s_nop 0
	v_addc_co_u32_e32 v9, vcc, 0, v5, vcc
	global_load_dword v38, v[6:7], off offset:1024
	global_load_dword v39, v[6:7], off offset:2048
	global_load_dword v43, v[6:7], off offset:3072
	global_load_dword v44, v[10:11], off offset:1024
	global_load_dword v45, v[10:11], off offset:2048
	global_load_dword v46, v[10:11], off offset:3072
	global_load_dword v47, v[8:9], off offset:1024
	global_load_dword v48, v[8:9], off offset:2048
	v_add_co_u32_e32 v14, vcc, s0, v4
	s_mov_b32 s0, 0x18206000
	s_nop 0
	v_addc_co_u32_e32 v15, vcc, 0, v5, vcc
	v_add_co_u32_e32 v6, vcc, s0, v4
	s_mov_b32 s0, 0x18207000
	s_nop 0
	v_addc_co_u32_e32 v7, vcc, 0, v5, vcc
	v_add_co_u32_e32 v10, vcc, s0, v4
	s_mov_b32 s0, 0x18208000
	s_nop 0
	v_addc_co_u32_e32 v11, vcc, 0, v5, vcc
	global_load_dword v49, v[12:13], off offset:2048
	global_load_dword v50, v[12:13], off offset:3072
	global_load_dword v51, v[14:15], off offset:-4096
	global_load_dword v52, v[14:15], off
	global_load_dword v53, v[14:15], off offset:1024
	global_load_dword v54, v[14:15], off offset:2048
	global_load_dword v55, v[14:15], off offset:3072
	global_load_dword v56, v[10:11], off offset:-4096
	v_add_co_u32_e32 v12, vcc, s0, v4
	s_mov_b32 s0, 0x18209000
	s_nop 0
	v_addc_co_u32_e32 v13, vcc, 0, v5, vcc
	v_add_co_u32_e32 v14, vcc, s0, v4
	s_mov_b32 s0, 0x1820a000
	s_nop 0
	v_addc_co_u32_e32 v15, vcc, 0, v5, vcc
	global_load_dword v57, v[10:11], off
	global_load_dword v58, v[10:11], off offset:1024
	global_load_dword v59, v[10:11], off offset:2048
	global_load_dword v60, v[10:11], off offset:3072
	global_load_dword v61, v[14:15], off offset:-4096
	global_load_dword v62, v[14:15], off
	global_load_dword v63, v[14:15], off offset:1024
	global_load_dword v64, v[14:15], off offset:2048
	v_add_co_u32_e32 v10, vcc, s0, v4
	s_mov_b32 s0, 0x1820b000
	s_nop 0
	v_addc_co_u32_e32 v11, vcc, 0, v5, vcc
	v_add_co_u32_e32 v16, vcc, s0, v4
	s_mov_b32 s0, 0x1820c000
	s_nop 0
	v_addc_co_u32_e32 v17, vcc, 0, v5, vcc
	global_load_dword v65, v[8:9], off offset:3072
	global_load_dword v66, v[6:7], off offset:1024
	global_load_dword v67, v[6:7], off offset:2048
	global_load_dword v68, v[6:7], off offset:3072
	global_load_dword v69, v[12:13], off offset:1024
	global_load_dword v70, v[12:13], off offset:2048
	global_load_dword v71, v[12:13], off offset:3072
	global_load_dword v72, v[10:11], off offset:1024
	v_add_co_u32_e32 v6, vcc, s0, v4
	s_mov_b32 s0, 0x1820d000
	s_nop 0
	v_addc_co_u32_e32 v7, vcc, 0, v5, vcc
	v_add_co_u32_e32 v20, vcc, s0, v4
	s_mov_b32 s0, 0x1820e000
	s_nop 0
	v_addc_co_u32_e32 v21, vcc, 0, v5, vcc
	v_add_co_u32_e32 v8, vcc, s0, v4
	s_mov_b32 s0, 0x1820f000
	s_nop 0
	v_addc_co_u32_e32 v9, vcc, 0, v5, vcc
	v_add_co_u32_e32 v4, vcc, s0, v4
	s_mov_b32 s0, 0xbfb8aa3b
	global_load_dword v73, v[14:15], off offset:3072
	global_load_dword v74, v[16:17], off offset:-4096
	global_load_dword v42, v[16:17], off
	global_load_dword v41, v[16:17], off offset:1024
	global_load_dword v40, v[16:17], off offset:2048
	global_load_dword v36, v[16:17], off offset:3072
	global_load_dword v34, v[20:21], off offset:-4096
	global_load_dword v25, v[20:21], off
	global_load_dword v75, v[10:11], off offset:2048
	global_load_dword v76, v[10:11], off offset:3072
	global_load_dword v37, v[6:7], off offset:1024
	global_load_dword v33, v[6:7], off offset:2048
	global_load_dword v31, v[6:7], off offset:3072
	global_load_dword v19, v[8:9], off offset:1024
	global_load_dword v16, v[8:9], off offset:2048
	global_load_dword v14, v[8:9], off offset:3072
	v_addc_co_u32_e32 v5, vcc, 0, v5, vcc
	global_load_dword v30, v[20:21], off offset:1024
	global_load_dword v28, v[20:21], off offset:2048
	global_load_dword v26, v[20:21], off offset:3072
	global_load_dword v24, v[4:5], off offset:-4096
	global_load_dword v15, v[4:5], off
	global_load_dword v13, v[4:5], off offset:1024
	global_load_dword v10, v[4:5], off offset:2048
	global_load_dword v9, v[4:5], off offset:3072
	s_ashr_i32 s5, s4, 31
	s_waitcnt vmcnt(62)
; __device__ __forceinline__ void phase_shift_cum(const Args& A, int gtid, int NGT, int gw, int lane) {
;     ...
;         float loc = 0.f;
; #pragma unroll
;         for (int i = 0; i < 64; ++i) { const float z = zv[i] + bf; loc += fminf(z, 0.f) - 0.6931471805599453f * __builtin_amdgcn_logf(1.0f + __builtin_amdgcn_exp2f(-1.4426950408889634f * fabsf(z))); zv[i] = loc; }
	v_add_f32_e32 v0, v3, v0
	v_mul_f32_e64 v6, |v0|, s0
	v_exp_f32_e32 v6, v6
	v_min_f32_e32 v0, 0, v0
	s_waitcnt vmcnt(60)
	v_add_f32_e32 v17, v3, v23
	s_waitcnt vmcnt(55)
	v_add_f32_e32 v5, v3, v38
	v_add_f32_e32 v4, 1.0, v6
	v_mul_f32_e64 v6, |v5|, s0
	v_log_f32_e32 v4, v4
	v_exp_f32_e32 v6, v6
	s_waitcnt vmcnt(53)
	v_add_f32_e32 v8, v3, v43
	v_mul_f32_e64 v11, |v8|, s0
	v_fmac_f32_e32 v0, 0xbf317218, v4
	v_min_f32_e32 v4, 0, v5
	v_add_f32_e32 v5, 1.0, v6
	v_add_f32_e32 v6, v3, v39
	v_mul_f32_e64 v7, |v6|, s0
	v_log_f32_e32 v5, v5
	v_exp_f32_e32 v7, v7
	v_exp_f32_e32 v11, v11
	s_waitcnt vmcnt(52)
	v_add_f32_e32 v21, v3, v44
	v_fmac_f32_e32 v4, 0xbf317218, v5
	v_add_f32_e32 v5, 1.0, v7
	v_log_f32_e32 v7, v5
	v_add_f32_e32 v5, 1.0, v11
	v_log_f32_e32 v11, v5
	v_min_f32_e32 v5, 0, v6
	v_fmac_f32_e32 v5, 0xbf317218, v7
	v_min_f32_e32 v6, 0, v8
	v_add_f32_e32 v7, v3, v18
	v_fmac_f32_e32 v6, 0xbf317218, v11
	v_mul_f32_e64 v8, |v7|, s0
	v_add_f32_e32 v11, v3, v22
	v_exp_f32_e32 v8, v8
	v_mul_f32_e64 v12, |v11|, s0
	v_exp_f32_e32 v12, v12
	v_mul_f32_e64 v18, |v17|, s0
	v_add_f32_e32 v8, 1.0, v8
	v_log_f32_e32 v8, v8
	v_add_f32_e32 v12, 1.0, v12
	v_exp_f32_e32 v18, v18
	v_log_f32_e32 v12, v12
	v_min_f32_e32 v7, 0, v7
	v_fmac_f32_e32 v7, 0xbf317218, v8
	v_min_f32_e32 v8, 0, v11
	v_add_f32_e32 v11, 1.0, v18
	v_add_f32_e32 v18, v3, v27
	v_fmac_f32_e32 v8, 0xbf317218, v12
	v_log_f32_e32 v12, v11
	v_mul_f32_e64 v11, |v18|, s0
	v_exp_f32_e32 v20, v11
	v_min_f32_e32 v11, 0, v17
	v_fmac_f32_e32 v11, 0xbf317218, v12
	v_min_f32_e32 v12, 0, v18
	v_add_f32_e32 v18, v3, v29
	v_add_f32_e32 v17, 1.0, v20
	v_mul_f32_e64 v20, |v18|, s0
	v_log_f32_e32 v17, v17
	v_exp_f32_e32 v20, v20
	v_mul_f32_e64 v22, |v21|, s0
	v_exp_f32_e32 v22, v22
	v_fmac_f32_e32 v12, 0xbf317218, v17
	v_add_f32_e32 v17, 1.0, v20
	v_log_f32_e32 v20, v17
	v_add_f32_e32 v17, 1.0, v22
	v_log_f32_e32 v22, v17
	v_min_f32_e32 v17, 0, v18
	v_fmac_f32_e32 v17, 0xbf317218, v20
	v_min_f32_e32 v18, 0, v21
	s_waitcnt vmcnt(51)
	v_add_f32_e32 v20, v3, v45
	v_fmac_f32_e32 v18, 0xbf317218, v22
	v_mul_f32_e64 v21, |v20|, s0
	s_waitcnt vmcnt(50)
	v_add_f32_e32 v22, v3, v46
	v_exp_f32_e32 v21, v21
	v_mul_f32_e64 v23, |v22|, s0
	v_exp_f32_e32 v23, v23
	v_add_f32_e32 v27, v3, v32
	v_add_f32_e32 v21, 1.0, v21
	v_mul_f32_e64 v29, |v27|, s0
	v_log_f32_e32 v21, v21
	v_add_f32_e32 v23, 1.0, v23
	v_exp_f32_e32 v29, v29
	v_log_f32_e32 v23, v23
	v_min_f32_e32 v20, 0, v20
	v_fmac_f32_e32 v20, 0xbf317218, v21
	v_min_f32_e32 v21, 0, v22
	v_add_f32_e32 v22, 1.0, v29
	v_add_f32_e32 v29, v3, v35
	v_fmac_f32_e32 v21, 0xbf317218, v23
	v_log_f32_e32 v23, v22
	v_mul_f32_e64 v22, |v29|, s0
	v_exp_f32_e32 v32, v22
	v_min_f32_e32 v22, 0, v27
	v_fmac_f32_e32 v22, 0xbf317218, v23
	v_min_f32_e32 v23, 0, v29
	s_waitcnt vmcnt(47)
	v_add_f32_e32 v29, v3, v49
	v_add_f32_e32 v27, 1.0, v32
	v_mul_f32_e64 v32, |v29|, s0
	s_waitcnt vmcnt(46)
	v_add_f32_e32 v35, v3, v50
	v_log_f32_e32 v27, v27
	v_exp_f32_e32 v32, v32
	v_mul_f32_e64 v38, |v35|, s0
	v_exp_f32_e32 v38, v38
	v_fmac_f32_e32 v23, 0xbf317218, v27
	v_add_f32_e32 v27, 1.0, v32
	v_log_f32_e32 v32, v27
	v_add_f32_e32 v27, 1.0, v38
	v_log_f32_e32 v38, v27
	v_min_f32_e32 v27, 0, v29
	v_fmac_f32_e32 v27, 0xbf317218, v32
	v_min_f32_e32 v29, 0, v35
	s_waitcnt vmcnt(45)
	v_add_f32_e32 v32, v3, v51
	v_fmac_f32_e32 v29, 0xbf317218, v38
	v_mul_f32_e64 v35, |v32|, s0
	v_add_f32_e32 v38, v3, v47
	v_exp_f32_e32 v35, v35
	v_mul_f32_e64 v39, |v38|, s0
	v_exp_f32_e32 v39, v39
	v_add_f32_e32 v43, v3, v48
	v_add_f32_e32 v35, 1.0, v35
	v_mul_f32_e64 v44, |v43|, s0
	v_log_f32_e32 v35, v35
	v_add_f32_e32 v39, 1.0, v39
	v_exp_f32_e32 v44, v44
	v_log_f32_e32 v39, v39
	v_min_f32_e32 v32, 0, v32
	v_fmac_f32_e32 v32, 0xbf317218, v35
	v_min_f32_e32 v35, 0, v38
	v_add_f32_e32 v38, 1.0, v44
	s_waitcnt vmcnt(31)
	v_add_f32_e32 v44, v3, v65
	v_fmac_f32_e32 v35, 0xbf317218, v39
	v_log_f32_e32 v39, v38
	v_mul_f32_e64 v38, |v44|, s0
	v_exp_f32_e32 v45, v38
	v_min_f32_e32 v38, 0, v43
	v_fmac_f32_e32 v38, 0xbf317218, v39
	v_min_f32_e32 v39, 0, v44
	v_add_f32_e32 v44, v3, v52
	v_add_f32_e32 v43, 1.0, v45
	v_mul_f32_e64 v45, |v44|, s0
	v_add_f32_e32 v46, v3, v53
	v_log_f32_e32 v43, v43
	v_exp_f32_e32 v45, v45
	v_mul_f32_e64 v47, |v46|, s0
	v_exp_f32_e32 v47, v47
	v_fmac_f32_e32 v39, 0xbf317218, v43
	v_add_f32_e32 v43, 1.0, v45
	v_log_f32_e32 v45, v43
	v_add_f32_e32 v43, 1.0, v47
	v_log_f32_e32 v47, v43
	v_min_f32_e32 v43, 0, v44
	v_fmac_f32_e32 v43, 0xbf317218, v45
	v_min_f32_e32 v44, 0, v46
	v_add_f32_e32 v45, v3, v54
	v_fmac_f32_e32 v44, 0xbf317218, v47
	v_mul_f32_e64 v46, |v45|, s0
	v_add_f32_e32 v47, v3, v55
	v_exp_f32_e32 v46, v46
	v_mul_f32_e64 v48, |v47|, s0
	v_exp_f32_e32 v48, v48
	v_add_f32_e32 v49, v3, v56
	v_add_f32_e32 v46, 1.0, v46
	v_log_f32_e32 v46, v46
	v_add_f32_e32 v48, 1.0, v48
	v_log_f32_e32 v48, v48
	v_mul_f32_e64 v50, |v49|, s0
	v_exp_f32_e32 v50, v50
	v_min_f32_e32 v45, 0, v45
	v_fmac_f32_e32 v45, 0xbf317218, v46
	v_min_f32_e32 v46, 0, v47
	v_fmac_f32_e32 v46, 0xbf317218, v48
	s_waitcnt vmcnt(30)
	v_add_f32_e32 v48, v3, v66
	v_add_f32_e32 v47, 1.0, v50
	v_mul_f32_e64 v50, |v48|, s0
	v_log_f32_e32 v47, v47
	v_exp_f32_e32 v50, v50
	v_min_f32_e32 v49, 0, v49
	s_waitcnt vmcnt(28)
; __device__ __forceinline__ void phase_shift_cum(const Args& A, int gtid, int NGT, int gw, int lane) {
;     ...
;         for (int i = 0; i < 64; ++i) { const float z = zv[i] + bf; loc += fminf(z, 0.f) - 0.6931471805599453f * __builtin_amdgcn_logf(1.0f + __builtin_amdgcn_exp2f(-1.4426950408889634f * fabsf(z))); zv[i] = loc; }
	v_add_f32_e32 v52, v3, v68
	v_fmac_f32_e32 v49, 0xbf317218, v47
	v_min_f32_e32 v47, 0, v48
	v_add_f32_e32 v48, 1.0, v50
	v_add_f32_e32 v50, v3, v67
	v_mul_f32_e64 v51, |v50|, s0
	v_log_f32_e32 v48, v48
	v_exp_f32_e32 v51, v51
	v_mul_f32_e64 v53, |v52|, s0
	v_exp_f32_e32 v53, v53
	v_fmac_f32_e32 v47, 0xbf317218, v48
	v_add_f32_e32 v48, 1.0, v51
	v_log_f32_e32 v48, v48
	v_add_f32_e32 v51, 1.0, v53
	v_log_f32_e32 v51, v51
	v_min_f32_e32 v50, 0, v50
	v_fmac_f32_e32 v50, 0xbf317218, v48
	v_min_f32_e32 v48, 0, v52
	v_fmac_f32_e32 v48, 0xbf317218, v51
	v_add_f32_e32 v51, v3, v57
	v_mul_f32_e64 v52, |v51|, s0
	v_add_f32_e32 v53, v3, v58
	v_exp_f32_e32 v52, v52
	v_mul_f32_e64 v54, |v53|, s0
	v_exp_f32_e32 v54, v54
	v_add_f32_e32 v55, v3, v59
	v_add_f32_e32 v52, 1.0, v52
	v_log_f32_e32 v52, v52
	v_add_f32_e32 v54, 1.0, v54
	v_log_f32_e32 v54, v54
	v_mul_f32_e64 v56, |v55|, s0
	v_exp_f32_e32 v56, v56
	v_min_f32_e32 v51, 0, v51
	v_fmac_f32_e32 v51, 0xbf317218, v52
	v_min_f32_e32 v52, 0, v53
	v_fmac_f32_e32 v52, 0xbf317218, v54
	v_add_f32_e32 v54, v3, v60
	v_add_f32_e32 v53, 1.0, v56
	v_mul_f32_e64 v56, |v54|, s0
	v_log_f32_e32 v53, v53
	v_exp_f32_e32 v56, v56
	v_min_f32_e32 v55, 0, v55
	s_waitcnt vmcnt(27)
	v_add_f32_e32 v58, v3, v69
	v_fmac_f32_e32 v55, 0xbf317218, v53
	v_min_f32_e32 v53, 0, v54
	v_add_f32_e32 v54, 1.0, v56
	v_add_f32_e32 v56, v3, v61
	v_mul_f32_e64 v57, |v56|, s0
	v_log_f32_e32 v54, v54
	v_exp_f32_e32 v57, v57
	v_mul_f32_e64 v59, |v58|, s0
	v_exp_f32_e32 v59, v59
	v_fmac_f32_e32 v53, 0xbf317218, v54
	v_add_f32_e32 v54, 1.0, v57
	v_log_f32_e32 v54, v54
	v_add_f32_e32 v57, 1.0, v59
	v_log_f32_e32 v57, v57
	v_min_f32_e32 v56, 0, v56
	v_fmac_f32_e32 v56, 0xbf317218, v54
	v_min_f32_e32 v54, 0, v58
	v_fmac_f32_e32 v54, 0xbf317218, v57
	s_waitcnt vmcnt(26)
	v_add_f32_e32 v57, v3, v70
	v_mul_f32_e64 v58, |v57|, s0
	s_waitcnt vmcnt(25)
	v_add_f32_e32 v59, v3, v71
	v_exp_f32_e32 v58, v58
	v_mul_f32_e64 v60, |v59|, s0
	v_exp_f32_e32 v60, v60
	v_add_f32_e32 v61, v3, v62
	v_add_f32_e32 v58, 1.0, v58
	v_log_f32_e32 v58, v58
	v_add_f32_e32 v60, 1.0, v60
	v_log_f32_e32 v60, v60
	v_mul_f32_e64 v62, |v61|, s0
	v_exp_f32_e32 v62, v62
	v_min_f32_e32 v57, 0, v57
	v_fmac_f32_e32 v57, 0xbf317218, v58
	v_min_f32_e32 v58, 0, v59
	v_fmac_f32_e32 v58, 0xbf317218, v60
	v_add_f32_e32 v60, v3, v63
	v_add_f32_e32 v59, 1.0, v62
	v_mul_f32_e64 v62, |v60|, s0
	v_log_f32_e32 v59, v59
	v_exp_f32_e32 v62, v62
	v_min_f32_e32 v61, 0, v61
	s_waitcnt vmcnt(15)
	v_add_f32_e32 v67, v3, v75
	v_fmac_f32_e32 v61, 0xbf317218, v59
	v_min_f32_e32 v59, 0, v60
	v_add_f32_e32 v60, 1.0, v62
	v_add_f32_e32 v62, v3, v64
	v_mul_f32_e64 v63, |v62|, s0
	v_add_f32_e32 v64, v3, v73
	v_log_f32_e32 v60, v60
	v_exp_f32_e32 v63, v63
	v_mul_f32_e64 v65, |v64|, s0
	v_exp_f32_e32 v65, v65
	v_fmac_f32_e32 v59, 0xbf317218, v60
	v_add_f32_e32 v60, 1.0, v63
	v_log_f32_e32 v60, v60
	v_add_f32_e32 v63, 1.0, v65
	v_log_f32_e32 v63, v63
	v_min_f32_e32 v62, 0, v62
	v_fmac_f32_e32 v62, 0xbf317218, v60
	v_min_f32_e32 v60, 0, v64
	v_fmac_f32_e32 v60, 0xbf317218, v63
	v_add_f32_e32 v63, v3, v74
	v_mul_f32_e64 v64, |v63|, s0
	v_add_f32_e32 v65, v3, v72
	v_exp_f32_e32 v64, v64
	v_mul_f32_e64 v66, |v65|, s0
	v_exp_f32_e32 v66, v66
	v_mul_f32_e64 v68, |v67|, s0
	v_add_f32_e32 v64, 1.0, v64
	v_log_f32_e32 v64, v64
	v_add_f32_e32 v66, 1.0, v66
	v_log_f32_e32 v66, v66
	v_exp_f32_e32 v68, v68
	v_min_f32_e32 v63, 0, v63
	v_fmac_f32_e32 v63, 0xbf317218, v64
	v_min_f32_e32 v64, 0, v65
	v_fmac_f32_e32 v64, 0xbf317218, v66
	s_waitcnt vmcnt(14)
	v_add_f32_e32 v66, v3, v76
	v_add_f32_e32 v65, 1.0, v68
	v_mul_f32_e64 v68, |v66|, s0
	v_log_f32_e32 v65, v65
	v_exp_f32_e32 v68, v68
	v_min_f32_e32 v67, 0, v67
	v_add_f32_e32 v42, v3, v42
	v_fmac_f32_e32 v67, 0xbf317218, v65
	v_min_f32_e32 v65, 0, v66
	v_add_f32_e32 v66, 1.0, v68
	v_mul_f32_e64 v68, |v42|, s0
	v_log_f32_e32 v66, v66
	v_exp_f32_e32 v68, v68
	v_add_f32_e32 v41, v3, v41
	v_mul_f32_e64 v69, |v41|, s0
	v_exp_f32_e32 v69, v69
	v_fmac_f32_e32 v65, 0xbf317218, v66
	v_add_f32_e32 v66, 1.0, v68
	v_log_f32_e32 v66, v66
	v_add_f32_e32 v68, 1.0, v69
	v_min_f32_e32 v69, 0, v42
	v_add_f32_e32 v40, v3, v40
	v_add_f32_e32 v36, v3, v36
	v_fmac_f32_e32 v69, 0xbf317218, v66
	v_min_f32_e32 v66, 0, v41
	v_mul_f32_e64 v41, |v40|, s0
	v_mul_f32_e64 v42, |v36|, s0
	v_log_f32_e32 v68, v68
	v_exp_f32_e32 v41, v41
	v_exp_f32_e32 v42, v42
	v_add_f32_e32 v34, v3, v34
	v_fmac_f32_e32 v66, 0xbf317218, v68
	v_min_f32_e32 v68, 0, v40
	v_add_f32_e32 v40, 1.0, v41
	v_add_f32_e32 v41, 1.0, v42
	v_mul_f32_e64 v42, |v34|, s0
	v_exp_f32_e32 v42, v42
	v_min_f32_e32 v70, 0, v36
	v_log_f32_e32 v40, v40
	s_waitcnt vmcnt(13)
	v_add_f32_e32 v37, v3, v37
	v_add_f32_e32 v36, 1.0, v42
	v_log_f32_e32 v36, v36
	v_min_f32_e32 v71, 0, v34
	s_waitcnt vmcnt(12)
	v_add_f32_e32 v33, v3, v33
	s_waitcnt vmcnt(11)
	v_add_f32_e32 v31, v3, v31
	v_add_f32_e32 v25, v3, v25
	s_waitcnt vmcnt(7)
	v_add_f32_e32 v30, v3, v30
	v_fmac_f32_e32 v68, 0xbf317218, v40
	v_mul_f32_e64 v40, |v37|, s0
	v_fmac_f32_e32 v71, 0xbf317218, v36
	v_min_f32_e32 v72, 0, v37
	v_mul_f32_e64 v36, |v33|, s0
	v_mul_f32_e64 v37, |v31|, s0
	v_min_f32_e32 v73, 0, v33
	v_min_f32_e32 v74, 0, v31
	v_mul_f32_e64 v31, |v25|, s0
	v_mul_f32_e64 v33, |v30|, s0
	v_exp_f32_e32 v31, v31
	v_exp_f32_e32 v33, v33
	s_waitcnt vmcnt(6)
	v_add_f32_e32 v28, v3, v28
	s_waitcnt vmcnt(5)
	v_add_f32_e32 v26, v3, v26
	s_waitcnt vmcnt(4)
; __device__ __forceinline__ void phase_shift_cum(const Args& A, int gtid, int NGT, int gw, int lane) {
;     ...
;         for (int i = 0; i < 64; ++i) { const float z = zv[i] + bf; loc += fminf(z, 0.f) - 0.6931471805599453f * __builtin_amdgcn_logf(1.0f + __builtin_amdgcn_exp2f(-1.4426950408889634f * fabsf(z))); zv[i] = loc; }
;         float incl = loc;
; #pragma unroll
;         for (int o = 1; o < 64; o <<= 1) { const float n = __shfl_up(incl, o); if (lane >= o) incl += n; }
	v_add_f32_e32 v24, v3, v24
	v_add_f32_e32 v19, v3, v19
	v_add_f32_e32 v16, v3, v16
	v_add_f32_e32 v14, v3, v14
	v_min_f32_e32 v75, 0, v25
	v_add_f32_e32 v25, 1.0, v31
	v_add_f32_e32 v31, 1.0, v33
	v_mul_f32_e64 v33, |v28|, s0
	v_min_f32_e32 v76, 0, v30
	v_mul_f32_e64 v30, |v26|, s0
	v_min_f32_e32 v77, 0, v28
	v_min_f32_e32 v78, 0, v26
	v_mul_f32_e64 v26, |v24|, s0
	v_mul_f32_e64 v28, |v19|, s0
	v_min_f32_e32 v79, 0, v24
	v_min_f32_e32 v80, 0, v19
	v_mul_f32_e64 v19, |v16|, s0
	v_mul_f32_e64 v24, |v14|, s0
	v_exp_f32_e32 v19, v19
	v_exp_f32_e32 v24, v24
	s_waitcnt vmcnt(3)
	v_add_f32_e32 v15, v3, v15
	v_min_f32_e32 v81, 0, v16
	v_add_f32_e32 v16, 1.0, v19
	v_add_f32_e32 v19, 1.0, v24
	v_mul_f32_e64 v24, |v15|, s0
	v_log_f32_e32 v16, v16
	v_exp_f32_e32 v24, v24
	s_waitcnt vmcnt(2)
	v_add_f32_e32 v13, v3, v13
	s_waitcnt vmcnt(1)
	v_add_f32_e32 v10, v3, v10
	s_waitcnt vmcnt(0)
	v_add_f32_e32 v3, v3, v9
	v_mul_f32_e64 v9, |v3|, s0
	v_fmac_f32_e32 v81, 0xbf317218, v16
	v_min_f32_e32 v82, 0, v14
	v_add_f32_e32 v14, 1.0, v24
	v_mul_f32_e64 v16, |v13|, s0
	v_exp_f32_e32 v9, v9
	v_log_f32_e32 v14, v14
	v_exp_f32_e32 v16, v16
	v_min_f32_e32 v83, 0, v15
	v_add_f32_e32 v9, 1.0, v9
	v_fmac_f32_e32 v83, 0xbf317218, v14
	v_min_f32_e32 v84, 0, v13
	v_add_f32_e32 v13, 1.0, v16
	v_mul_f32_e64 v14, |v10|, s0
	v_log_f32_e32 v9, v9
	v_log_f32_e32 v13, v13
	v_exp_f32_e32 v14, v14
	v_min_f32_e32 v3, 0, v3
	v_fmac_f32_e32 v3, 0xbf317218, v9
	v_mbcnt_lo_u32_b32 v9, -1, 0
	v_fmac_f32_e32 v84, 0xbf317218, v13
	v_add_f32_e32 v13, 1.0, v14
	v_mbcnt_hi_u32_b32 v86, -1, v9
	v_add_f32_e32 v14, 0, v0
	v_and_b32_e32 v87, 64, v86
	v_add_u32_e32 v9, -1, v86
	v_add_f32_e32 v15, v14, v4
	v_log_f32_e32 v25, v25
	v_exp_f32_e32 v33, v33
	v_cmp_lt_i32_e32 vcc, v9, v87
	v_add_f32_e32 v4, v15, v5
	v_add_f32_e32 v5, v4, v6
	v_cndmask_b32_e32 v9, v9, v86, vcc
	v_lshlrev_b32_e32 v88, 2, v9
	v_add_u32_e32 v9, -2, v86
	v_add_f32_e32 v6, v5, v7
	v_cmp_lt_i32_e32 vcc, v9, v87
	v_add_f32_e32 v7, v6, v8
	v_fmac_f32_e32 v75, 0xbf317218, v25
	v_add_f32_e32 v25, 1.0, v33
	v_cndmask_b32_e32 v9, v9, v86, vcc
	v_add_f32_e32 v8, v7, v11
	v_log_f32_e32 v25, v25
	v_exp_f32_e32 v30, v30
	v_log_f32_e32 v13, v13
	v_lshlrev_b32_e32 v89, 2, v9
	v_add_f32_e32 v9, v8, v12
	v_min_f32_e32 v85, 0, v10
	v_add_f32_e32 v10, v9, v17
	v_add_f32_e32 v11, v10, v18
	v_add_f32_e32 v12, v11, v20
	v_fmac_f32_e32 v77, 0xbf317218, v25
	v_add_f32_e32 v25, 1.0, v30
	v_log_f32_e32 v19, v19
	v_fmac_f32_e32 v85, 0xbf317218, v13
	v_add_f32_e32 v13, v12, v21
	v_log_f32_e32 v25, v25
	v_exp_f32_e32 v26, v26
	v_add_f32_e32 v16, v13, v22
	v_exp_f32_e32 v28, v28
	v_add_f32_e32 v17, v16, v23
	v_add_f32_e32 v18, v17, v27
	v_fmac_f32_e32 v82, 0xbf317218, v19
	v_add_f32_e32 v19, v18, v29
	v_exp_f32_e32 v40, v40
	v_fmac_f32_e32 v78, 0xbf317218, v25
	v_add_f32_e32 v25, 1.0, v26
	v_add_f32_e32 v20, v19, v32
	v_log_f32_e32 v25, v25
	v_add_f32_e32 v26, 1.0, v28
	v_add_f32_e32 v21, v20, v35
	v_log_f32_e32 v26, v26
	v_add_f32_e32 v22, v21, v38
	v_add_f32_e32 v23, v22, v39
	v_add_f32_e32 v34, 1.0, v40
	v_add_f32_e32 v24, v23, v43
	v_log_f32_e32 v34, v34
	v_exp_f32_e32 v36, v36
	v_fmac_f32_e32 v79, 0xbf317218, v25
	v_add_f32_e32 v25, v24, v44
	v_fmac_f32_e32 v80, 0xbf317218, v26
	v_add_f32_e32 v26, v25, v45
	v_exp_f32_e32 v37, v37
	v_log_f32_e32 v31, v31
	v_add_f32_e32 v27, v26, v46
	v_add_f32_e32 v28, v27, v49
	v_fmac_f32_e32 v72, 0xbf317218, v34
	v_add_f32_e32 v34, 1.0, v36
	v_add_f32_e32 v29, v28, v47
	v_log_f32_e32 v34, v34
	v_add_f32_e32 v30, v29, v50
	v_add_f32_e32 v36, 1.0, v37
	v_fmac_f32_e32 v76, 0xbf317218, v31
	v_add_f32_e32 v31, v30, v48
	v_log_f32_e32 v36, v36
	v_add_f32_e32 v32, v31, v51
	v_add_f32_e32 v33, v32, v52
	v_fmac_f32_e32 v73, 0xbf317218, v34
	v_add_f32_e32 v34, v33, v55
	v_add_f32_e32 v35, v34, v53
	v_fmac_f32_e32 v74, 0xbf317218, v36
	v_add_f32_e32 v36, v35, v56
	v_log_f32_e32 v41, v41
	v_add_f32_e32 v37, v36, v54
	v_add_f32_e32 v38, v37, v57
	v_add_f32_e32 v39, v38, v58
	v_add_f32_e32 v40, v39, v61
	v_fmac_f32_e32 v70, 0xbf317218, v41
	v_add_f32_e32 v41, v40, v59
	v_add_f32_e32 v42, v41, v62
	v_add_f32_e32 v43, v42, v60
	v_add_f32_e32 v44, v43, v63
	v_add_f32_e32 v45, v44, v64
	v_add_f32_e32 v46, v45, v67
	v_add_f32_e32 v47, v46, v65
	v_add_f32_e32 v48, v47, v69
	v_add_f32_e32 v49, v48, v66
	v_add_f32_e32 v50, v49, v68
	v_add_f32_e32 v51, v50, v70
	v_add_f32_e32 v52, v51, v71
	v_add_f32_e32 v53, v52, v72
	v_add_f32_e32 v54, v53, v73
	v_add_f32_e32 v55, v54, v74
	v_add_f32_e32 v56, v55, v75
	v_add_f32_e32 v57, v56, v76
	v_add_f32_e32 v58, v57, v77
	v_add_f32_e32 v59, v58, v78
	v_add_f32_e32 v60, v59, v79
	v_add_f32_e32 v61, v60, v80
	v_add_f32_e32 v62, v61, v81
	v_add_f32_e32 v63, v62, v82
	v_add_f32_e32 v64, v63, v83
	v_add_f32_e32 v65, v64, v84
	v_add_f32_e32 v66, v65, v85
	v_add_f32_e32 v67, v66, v3
	ds_bpermute_b32 v0, v88, v67
	v_add_u32_e32 v90, -4, v86
	v_cmp_lt_i32_e32 vcc, v90, v87
	v_add_u32_e32 v68, -8, v86
	v_add_u32_e32 v70, -16, v86
	v_cndmask_b32_e32 v3, v90, v86, vcc
	s_waitcnt lgkmcnt(0)
; __device__ __forceinline__ void phase_shift_cum(const Args& A, int gtid, int NGT, int gw, int lane) {
;     ...
;         for (int o = 1; o < 64; o <<= 1) { const float n = __shfl_up(incl, o); if (lane >= o) incl += n; }
;         const float off = incl - loc; float* dst = CUM + (size_t)gw * T + lane * 64;
; #pragma unroll
;         for (int i = 0; i < 64; i += 4) *(f32x4*)(dst + i) = (f32x4){zv[i] + off, zv[i + 1] + off, zv[i + 2] + off, zv[i + 3] + off};
	v_add_f32_e32 v0, v67, v0
	v_cmp_eq_u32_e32 vcc, 0, v2
	v_lshlrev_b32_e32 v3, 2, v3
	s_lshl_b64 s[0:1], s[4:5], 14
	v_cndmask_b32_e32 v0, v0, v67, vcc
	ds_bpermute_b32 v69, v89, v0
	v_cmp_lt_i32_e32 vcc, v68, v87
	s_add_u32 s0, s34, s0
	s_addc_u32 s1, s35, s1
	v_cndmask_b32_e32 v68, v68, v86, vcc
	s_waitcnt lgkmcnt(0)
	v_add_f32_e32 v69, v0, v69
	v_cmp_gt_u32_e32 vcc, 2, v2
	v_lshlrev_b32_e32 v68, 2, v68
	s_nop 0
	v_cndmask_b32_e32 v0, v69, v0, vcc
	ds_bpermute_b32 v3, v3, v0
	v_cmp_lt_i32_e32 vcc, v70, v87
	s_waitcnt lgkmcnt(0)
	v_add_f32_e32 v3, v0, v3
	v_cndmask_b32_e32 v69, v70, v86, vcc
	v_cmp_gt_u32_e32 vcc, 4, v2
	v_subrev_u32_e32 v70, 32, v86
	v_lshlrev_b32_e32 v69, 2, v69
	v_cndmask_b32_e32 v0, v3, v0, vcc
	ds_bpermute_b32 v3, v68, v0
	v_cmp_lt_i32_e32 vcc, v70, v87
	s_waitcnt lgkmcnt(0)
	v_add_f32_e32 v3, v0, v3
	v_cndmask_b32_e32 v68, v70, v86, vcc
	v_cmp_gt_u32_e32 vcc, 8, v2
	v_lshlrev_b32_e32 v68, 2, v68
	s_nop 0
	v_cndmask_b32_e32 v3, v3, v0, vcc
	ds_bpermute_b32 v69, v69, v3
	v_cmp_gt_u32_e32 vcc, 16, v2
	v_lshlrev_b32_e32 v0, 8, v2
	s_waitcnt lgkmcnt(0)
	v_add_f32_e32 v69, v3, v69
	v_cndmask_b32_e32 v3, v69, v3, vcc
	ds_bpermute_b32 v72, v68, v3
	v_lshl_add_u64 v[68:69], s[0:1], 0, v[0:1]
	v_cmp_gt_u32_e32 vcc, 32, v2
	s_mov_b64 s[0:1], 0x28800000
	v_lshl_add_u64 v[70:71], v[68:69], 0, s[0:1]
	s_waitcnt lgkmcnt(0)
	v_add_f32_e32 v0, v3, v72
	v_cndmask_b32_e32 v0, v0, v3, vcc
	v_sub_f32_e32 v72, v0, v67
	s_mov_b32 s0, 0x28800000
	v_pk_add_f32 v[2:3], v[4:5], v[72:73] op_sel_hi:[1,0]
	v_add_co_u32_e32 v4, vcc, s0, v68
	v_pk_add_f32 v[0:1], v[14:15], v[72:73] op_sel_hi:[1,0]
	s_nop 0
	v_addc_co_u32_e32 v5, vcc, 0, v69, vcc
	global_store_dwordx4 v[4:5], v[0:3], off
	s_nop 1
	v_pk_add_f32 v[2:3], v[8:9], v[72:73] op_sel_hi:[1,0]
	v_pk_add_f32 v[0:1], v[6:7], v[72:73] op_sel_hi:[1,0]
	global_store_dwordx4 v[70:71], v[0:3], off offset:16
	s_nop 1
	v_pk_add_f32 v[2:3], v[12:13], v[72:73] op_sel_hi:[1,0]
	v_pk_add_f32 v[0:1], v[10:11], v[72:73] op_sel_hi:[1,0]
	global_store_dwordx4 v[70:71], v[0:3], off offset:32
	s_nop 1
	v_pk_add_f32 v[2:3], v[18:19], v[72:73] op_sel_hi:[1,0]
	v_pk_add_f32 v[0:1], v[16:17], v[72:73] op_sel_hi:[1,0]
	global_store_dwordx4 v[70:71], v[0:3], off offset:48
	s_nop 1
	v_pk_add_f32 v[2:3], v[22:23], v[72:73] op_sel_hi:[1,0]
	v_pk_add_f32 v[0:1], v[20:21], v[72:73] op_sel_hi:[1,0]
	global_store_dwordx4 v[70:71], v[0:3], off offset:64
	s_nop 1
	v_pk_add_f32 v[2:3], v[26:27], v[72:73] op_sel_hi:[1,0]
	v_pk_add_f32 v[0:1], v[24:25], v[72:73] op_sel_hi:[1,0]
	global_store_dwordx4 v[70:71], v[0:3], off offset:80
	s_nop 1
	v_pk_add_f32 v[2:3], v[30:31], v[72:73] op_sel_hi:[1,0]
	v_pk_add_f32 v[0:1], v[28:29], v[72:73] op_sel_hi:[1,0]
	global_store_dwordx4 v[70:71], v[0:3], off offset:96
	s_nop 1
	v_pk_add_f32 v[2:3], v[34:35], v[72:73] op_sel_hi:[1,0]
	v_pk_add_f32 v[0:1], v[32:33], v[72:73] op_sel_hi:[1,0]
	global_store_dwordx4 v[70:71], v[0:3], off offset:112
	s_nop 1
	v_pk_add_f32 v[2:3], v[38:39], v[72:73] op_sel_hi:[1,0]
	v_pk_add_f32 v[0:1], v[36:37], v[72:73] op_sel_hi:[1,0]
	global_store_dwordx4 v[70:71], v[0:3], off offset:128
	s_nop 1
	v_pk_add_f32 v[2:3], v[42:43], v[72:73] op_sel_hi:[1,0]
	v_pk_add_f32 v[0:1], v[40:41], v[72:73] op_sel_hi:[1,0]
	global_store_dwordx4 v[70:71], v[0:3], off offset:144
	s_nop 1
	v_pk_add_f32 v[2:3], v[46:47], v[72:73] op_sel_hi:[1,0]
	v_pk_add_f32 v[0:1], v[44:45], v[72:73] op_sel_hi:[1,0]
	global_store_dwordx4 v[70:71], v[0:3], off offset:160
	s_nop 1
	v_pk_add_f32 v[2:3], v[50:51], v[72:73] op_sel_hi:[1,0]
	v_pk_add_f32 v[0:1], v[48:49], v[72:73] op_sel_hi:[1,0]
	global_store_dwordx4 v[70:71], v[0:3], off offset:176
	s_nop 1
	v_pk_add_f32 v[2:3], v[54:55], v[72:73] op_sel_hi:[1,0]
	v_pk_add_f32 v[0:1], v[52:53], v[72:73] op_sel_hi:[1,0]
	global_store_dwordx4 v[70:71], v[0:3], off offset:192
	s_nop 1
	v_pk_add_f32 v[2:3], v[58:59], v[72:73] op_sel_hi:[1,0]
	v_pk_add_f32 v[0:1], v[56:57], v[72:73] op_sel_hi:[1,0]
	global_store_dwordx4 v[70:71], v[0:3], off offset:208
	s_nop 1
	v_pk_add_f32 v[2:3], v[62:63], v[72:73] op_sel_hi:[1,0]
	v_pk_add_f32 v[0:1], v[60:61], v[72:73] op_sel_hi:[1,0]
	global_store_dwordx4 v[70:71], v[0:3], off offset:224
	s_nop 1
	v_pk_add_f32 v[2:3], v[66:67], v[72:73] op_sel_hi:[1,0]
	v_pk_add_f32 v[0:1], v[64:65], v[72:73] op_sel_hi:[1,0]
	global_store_dwordx4 v[70:71], v[0:3], off offset:240
